# waves 4..7 convert one expert-weight item inside the wait of grid barriers 0..15 (16 x 1024 items taken off the two attention phases)
# baseline (speedup 1.0000x reference)
.Lsx_e_0:
	s_cmp_lt_u32 s33, 4
	s_cbranch_scc1 .LBB0_169
	s_lshl_b32 s16, s92, 2
	s_add_i32 s16, s16, s33
	s_add_i32 s16, s16, 0x27fc
	s_mov_b32 s17, 0
	s_branch .Lsx_conv_A
.Lsx_e_1:
	s_cmp_lt_u32 s33, 4
	s_cbranch_scc1 .LBB0_238
	s_lshl_b32 s16, s92, 2
	s_add_i32 s16, s16, s33
	s_add_i32 s16, s16, 0x2bfc
	s_mov_b32 s17, 1
	s_branch .Lsx_conv_A
.Lsx_e_2:
	s_cmp_lt_u32 s33, 4
	s_cbranch_scc1 .LBB0_654
	s_lshl_b32 s16, s92, 2
	s_add_i32 s16, s16, s33
	s_add_i32 s16, s16, 0x2ffc
	s_mov_b32 s17, 2
	s_branch .Lsx_conv_A
.Lsx_e_3:
	s_cmp_lt_u32 s33, 4
	s_cbranch_scc1 .LBB0_736
	s_lshl_b32 s16, s92, 2
	s_add_i32 s16, s16, s33
	s_add_i32 s16, s16, 0x33fc
	s_mov_b32 s17, 3
	s_branch .Lsx_conv_A
.Lsx_e_4:
	s_cmp_lt_u32 s33, 4
	s_cbranch_scc1 .LBB0_1099
	s_lshl_b32 s16, s92, 2
	s_add_i32 s16, s16, s33
	s_add_i32 s16, s16, 0x37fc
	s_mov_b32 s17, 4
	s_branch .Lsx_conv_A
.Lsx_e_5:
	s_cmp_lt_u32 s33, 4
	s_cbranch_scc1 .LBB0_1262
	s_lshl_b32 s16, s92, 2
	s_add_i32 s16, s16, s33
	s_add_i32 s16, s16, 0x3bfc
	s_mov_b32 s17, 5
	s_branch .Lsx_conv_A
.Lsx_e_6:
	s_cmp_lt_u32 s33, 4
	s_cbranch_scc1 .LBB0_1388
	s_lshl_b32 s16, s92, 2
	s_add_i32 s16, s16, s33
	s_add_i32 s16, s16, 0x3ffc
	s_mov_b32 s17, 6
	s_branch .Lsx_conv_A
.Lsx_e_7:
	s_cmp_lt_u32 s33, 4
	s_cbranch_scc1 .LBB0_1468
	s_lshl_b32 s16, s92, 2
	s_add_i32 s16, s16, s33
	s_add_i32 s16, s16, 0x43fc
	s_mov_b32 s17, 7
	s_branch .Lsx_conv_A
.Lsx_conv_A:
	s_mov_b64 exec, -1
	v_mbcnt_hi_u32_b32 v216, -1, v254
	v_mov_b32_e32 v213, 0
	s_mov_b32 s21, 0
	v_lshlrev_b32_e32 v216, 2, v216
	s_add_u32 s12, s58, 0x33d8000
	s_addc_u32 s13, s59, 0
	s_add_u32 s14, s58, 0x233d8000
	s_addc_u32 s15, s59, 0
	v_and_b32_e32 v217, 0x7c, v216
	s_ashr_i32 s20, s16, 10
	s_mul_hi_i32 s38, s20, 0x55555556
	s_lshr_b32 s39, s38, 31
	s_add_i32 s40, s38, s39
	s_mul_i32 s38, s40, 3
	s_sub_i32 s44, s20, s38
	s_lshl_b32 s20, s16, 8
	s_ashr_i32 s45, s44, 31
	s_and_b32 s20, s20, 0x700
	s_lshl_b64 s[38:39], s[44:45], 3
	s_add_u32 s42, s0, s38
	s_addc_u32 s43, s1, s39
	s_ashr_i32 s41, s40, 31
	v_or_b32_e32 v212, s20, v216
	s_cmp_lg_u32 s44, 2
	s_mov_b64 s[46:47], -1
	s_cbranch_scc0 .LsxA_1165
	v_lshlrev_b32_e32 v214, 1, v212
	s_lshl_b64 s[38:39], s[40:41], 23
	v_and_b32_e32 v214, 0xf00, v214
	v_lshl_or_b32 v215, s44, 7, v217
	s_add_u32 s38, s12, s38
	v_add_u32_e32 v214, v215, v214
	s_addc_u32 s39, s13, s39
	s_mov_b64 s[46:47], 0
.LsxA_1165:
	s_load_dwordx2 s[42:43], s[42:43], 0xc0
	s_andn2_b64 vcc, exec, s[46:47]
	s_lshl_b64 s[44:45], s[40:41], 22
	s_cbranch_vccnz .LsxA_1167
	s_add_u32 s38, s14, s44
	s_mov_b64 s[40:41], 0x800
	s_addc_u32 s39, s15, s45
	s_mov_b32 s41, 0x42800000
	v_mov_b32_e32 v214, v212
	s_branch .LsxA_1168

.LsxA_1168:
	s_lshl_b64 s[44:45], s[44:45], 2
	s_waitcnt lgkmcnt(0)
	s_add_u32 s20, s42, s44
	s_addc_u32 s43, s43, s45
	s_bfe_u32 s44, s16, 0x70003
	s_lshl_b32 s42, s44, 17
	s_add_u32 s42, s20, s42
	s_addc_u32 s43, s43, 0
	v_lshlrev_b32_e32 v212, 2, v212
	v_lshl_add_u64 v[144:145], s[42:43], 0, v[212:213]
	v_add_co_u32_e32 v88, vcc, 0x2000, v144
	global_load_dwordx4 v[84:87], v212, s[42:43] nt
	s_nop 0
	v_addc_co_u32_e32 v89, vcc, 0, v145, vcc
	v_add_co_u32_e32 v92, vcc, 0x4000, v144
	v_mov_b32_e32 v200, v213
	s_nop 0
	v_addc_co_u32_e32 v93, vcc, 0, v145, vcc
	v_add_co_u32_e32 v96, vcc, 0x6000, v144
	global_load_dwordx4 v[88:91], v[88:89], off nt
	s_nop 0
	global_load_dwordx4 v[92:95], v[92:93], off nt
	v_addc_co_u32_e32 v97, vcc, 0, v145, vcc
	v_add_co_u32_e32 v100, vcc, 0x8000, v144
	v_mov_b32_e32 v201, v213
	s_nop 0
	v_addc_co_u32_e32 v101, vcc, 0, v145, vcc
	v_add_co_u32_e32 v104, vcc, 0xa000, v144
	global_load_dwordx4 v[96:99], v[96:97], off nt
	s_nop 0
	global_load_dwordx4 v[100:103], v[100:101], off nt
	v_addc_co_u32_e32 v105, vcc, 0, v145, vcc
	v_add_co_u32_e32 v108, vcc, 0xc000, v144
	v_mov_b32_e32 v202, v213
	s_nop 0
	v_addc_co_u32_e32 v109, vcc, 0, v145, vcc
	v_add_co_u32_e32 v112, vcc, 0xe000, v144
	global_load_dwordx4 v[104:107], v[104:105], off nt
	s_nop 0
	global_load_dwordx4 v[108:111], v[108:109], off nt
	v_addc_co_u32_e32 v113, vcc, 0, v145, vcc
	v_add_co_u32_e32 v116, vcc, 0x10000, v144
	v_mov_b32_e32 v203, v213
	s_nop 0
	v_addc_co_u32_e32 v117, vcc, 0, v145, vcc
	v_add_co_u32_e32 v120, vcc, 0x12000, v144
	global_load_dwordx4 v[112:115], v[112:113], off nt
	s_nop 0
	global_load_dwordx4 v[116:119], v[116:117], off nt
	v_addc_co_u32_e32 v121, vcc, 0, v145, vcc
	v_add_co_u32_e32 v124, vcc, 0x14000, v144
	v_mov_b32_e32 v204, v213
	s_nop 0
	v_addc_co_u32_e32 v125, vcc, 0, v145, vcc
	v_add_co_u32_e32 v128, vcc, 0x16000, v144
	global_load_dwordx4 v[120:123], v[120:121], off nt
	s_nop 0
	global_load_dwordx4 v[124:127], v[124:125], off nt
	v_addc_co_u32_e32 v129, vcc, 0, v145, vcc
	v_add_co_u32_e32 v132, vcc, 0x18000, v144
	v_mov_b32_e32 v205, v213
	s_nop 0
	v_addc_co_u32_e32 v133, vcc, 0, v145, vcc
	v_add_co_u32_e32 v136, vcc, 0x1a000, v144
	global_load_dwordx4 v[128:131], v[128:129], off nt
	s_nop 0
	global_load_dwordx4 v[132:135], v[132:133], off nt
	v_addc_co_u32_e32 v137, vcc, 0, v145, vcc
	v_add_co_u32_e32 v140, vcc, 0x1c000, v144
	v_mov_b32_e32 v206, v213
	s_nop 0
	v_addc_co_u32_e32 v141, vcc, 0, v145, vcc
	global_load_dwordx4 v[136:139], v[136:137], off nt
	s_nop 0
	global_load_dwordx4 v[140:143], v[140:141], off nt
	v_add_co_u32_e32 v144, vcc, 0x1e000, v144
	v_mov_b32_e32 v207, v213
	s_nop 0
	v_addc_co_u32_e32 v145, vcc, 0, v145, vcc
	global_load_dwordx4 v[144:147], v[144:145], off nt
	v_mov_b32_e32 v208, v213
	v_mov_b32_e32 v209, v213
	v_mov_b32_e32 v210, v213
	v_mov_b32_e32 v211, v213
	s_mul_i32 s20, s40, s44
	s_waitcnt vmcnt(15)
	v_mul_f32_e32 v212, s41, v84
	v_ashrrev_i32_e32 v215, 31, v214
	v_lshl_add_u64 v[214:215], s[20:21], 0, v[214:215]
	v_lshl_add_u64 v[214:215], v[214:215], 4, s[38:39]
	s_waitcnt vmcnt(14)
	v_mul_f32_e32 v84, s41, v88
	v_cvt_pk_fp8_f32 v200, v212, v84
	s_waitcnt vmcnt(13)
	v_mul_f32_e32 v88, s41, v92
	s_waitcnt vmcnt(12)
	v_mul_f32_e32 v92, s41, v96
	s_waitcnt vmcnt(11)
	v_mul_f32_e32 v212, s41, v100
	v_cvt_pk_fp8_f32 v200, v88, v92 op_sel:[0,0,1]
	s_waitcnt vmcnt(10)
	v_mul_f32_e32 v84, s41, v104
	v_cvt_pk_fp8_f32 v201, v212, v84
	s_waitcnt vmcnt(9)
	v_mul_f32_e32 v212, s41, v108
	s_waitcnt vmcnt(8)
	v_mul_f32_e32 v84, s41, v112
	v_cvt_pk_fp8_f32 v201, v212, v84 op_sel:[0,0,1]
	s_waitcnt vmcnt(7)
	v_mul_f32_e32 v212, s41, v116
	s_waitcnt vmcnt(6)
	v_mul_f32_e32 v84, s41, v120
	v_cvt_pk_fp8_f32 v202, v212, v84
	s_waitcnt vmcnt(5)
	v_mul_f32_e32 v88, s41, v124
	s_waitcnt vmcnt(4)
	v_mul_f32_e32 v92, s41, v128
	s_waitcnt vmcnt(3)
	v_mul_f32_e32 v212, s41, v132
	v_cvt_pk_fp8_f32 v202, v88, v92 op_sel:[0,0,1]
	v_mul_f32_e32 v88, s41, v97
	s_waitcnt vmcnt(2)
	v_mul_f32_e32 v84, s41, v136
	v_cvt_pk_fp8_f32 v203, v212, v84
	s_waitcnt vmcnt(1)
	v_mul_f32_e32 v212, s41, v140
	s_waitcnt vmcnt(0)
	v_mul_f32_e32 v84, s41, v144
	v_cvt_pk_fp8_f32 v203, v212, v84 op_sel:[0,0,1]
	v_mul_f32_e32 v212, s41, v85
	v_mul_f32_e32 v84, s41, v89
	v_cvt_pk_fp8_f32 v204, v212, v84
	v_mul_f32_e32 v212, s41, v101
	v_mul_f32_e32 v84, s41, v105
	v_cvt_pk_fp8_f32 v205, v212, v84
	v_mul_f32_e32 v212, s41, v109
	v_mul_f32_e32 v84, s41, v113
	v_mul_f32_e32 v85, s41, v93
	v_cvt_pk_fp8_f32 v205, v212, v84 op_sel:[0,0,1]
	v_mul_f32_e32 v212, s41, v117
	v_mul_f32_e32 v84, s41, v121
	v_cvt_pk_fp8_f32 v206, v212, v84
	v_mul_f32_e32 v212, s41, v133
	v_mul_f32_e32 v84, s41, v137
	v_cvt_pk_fp8_f32 v207, v212, v84
	v_mul_f32_e32 v212, s41, v141
	v_mul_f32_e32 v84, s41, v145
	v_cvt_pk_fp8_f32 v204, v85, v88 op_sel:[0,0,1]
	v_cvt_pk_fp8_f32 v207, v212, v84 op_sel:[0,0,1]
	v_mul_f32_e32 v212, s41, v86
	v_mul_f32_e32 v84, s41, v90
	v_cvt_pk_fp8_f32 v208, v212, v84
	v_mul_f32_e32 v212, s41, v102
	v_mul_f32_e32 v84, s41, v106
	v_cvt_pk_fp8_f32 v209, v212, v84
	v_mul_f32_e32 v212, s41, v110
	v_mul_f32_e32 v84, s41, v114
	v_mul_f32_e32 v85, s41, v125
	v_cvt_pk_fp8_f32 v209, v212, v84 op_sel:[0,0,1]
	v_mul_f32_e32 v212, s41, v118
	v_mul_f32_e32 v84, s41, v122
	v_cvt_pk_fp8_f32 v210, v212, v84
	v_mul_f32_e32 v212, s41, v134
	v_mul_f32_e32 v84, s41, v138
	v_cvt_pk_fp8_f32 v211, v212, v84
	v_mul_f32_e32 v88, s41, v129
	v_cvt_pk_fp8_f32 v206, v85, v88 op_sel:[0,0,1]
	v_mul_f32_e32 v85, s41, v94
	v_mul_f32_e32 v86, s41, v98
	v_cvt_pk_fp8_f32 v208, v85, v86 op_sel:[0,0,1]
	v_mul_f32_e32 v85, s41, v126
	v_mul_f32_e32 v86, s41, v130
	v_mul_f32_e32 v212, s41, v142
	v_mul_f32_e32 v84, s41, v146
	v_cvt_pk_fp8_f32 v210, v85, v86 op_sel:[0,0,1]
	v_cvt_pk_fp8_f32 v211, v212, v84 op_sel:[0,0,1]
	v_mul_f32_e32 v212, s41, v87
	v_mul_f32_e32 v85, s41, v91
	v_mov_b32_e32 v84, v213
	v_cvt_pk_fp8_f32 v84, v212, v85
	v_mul_f32_e32 v212, s41, v103
	v_mul_f32_e32 v88, s41, v107
	v_mov_b32_e32 v85, v213
	v_cvt_pk_fp8_f32 v85, v212, v88
	v_mul_f32_e32 v86, s41, v95
	v_mul_f32_e32 v87, s41, v99
	v_cvt_pk_fp8_f32 v84, v86, v87 op_sel:[0,0,1]
	v_mul_f32_e32 v212, s41, v111
	v_mul_f32_e32 v86, s41, v115
	v_cvt_pk_fp8_f32 v85, v212, v86 op_sel:[0,0,1]
	v_mul_f32_e32 v212, s41, v119
	v_mul_f32_e32 v87, s41, v123
	v_mov_b32_e32 v86, v213
	v_cvt_pk_fp8_f32 v86, v212, v87
	v_mul_f32_e32 v212, s41, v135
	v_mul_f32_e32 v90, s41, v139
	v_mov_b32_e32 v87, v213
	v_cvt_pk_fp8_f32 v87, v212, v90
	v_mul_f32_e32 v88, s41, v127
	v_mul_f32_e32 v89, s41, v131
	v_cvt_pk_fp8_f32 v86, v88, v89 op_sel:[0,0,1]
	v_mul_f32_e32 v212, s41, v143
	v_mul_f32_e32 v88, s41, v147
	v_cvt_pk_fp8_f32 v87, v212, v88 op_sel:[0,0,1]
	global_store_dwordx4 v[214:215], v[200:203], off
	global_store_dwordx4 v[214:215], v[204:207], off offset:16
	global_store_dwordx4 v[214:215], v[208:211], off offset:32
	global_store_dwordx4 v[214:215], v[84:87], off offset:48
	s_cmp_eq_u32 s17, 0
	s_cbranch_scc1 .LBB0_169
	s_cmp_eq_u32 s17, 1
	s_cbranch_scc1 .LBB0_238
	s_cmp_eq_u32 s17, 2
	s_cbranch_scc1 .LBB0_654
	s_cmp_eq_u32 s17, 3
	s_cbranch_scc1 .LBB0_736
	s_cmp_eq_u32 s17, 4
	s_cbranch_scc1 .LBB0_1099
	s_cmp_eq_u32 s17, 5
	s_cbranch_scc1 .LBB0_1262
	s_cmp_eq_u32 s17, 6
	s_cbranch_scc1 .LBB0_1388
	s_cmp_eq_u32 s17, 7
	s_cbranch_scc1 .LBB0_1468
	s_branch .LBB0_1468

.LBB0_1133:
	s_andn2_b64 vcc, exec, s[6:7]
	s_cbranch_vccnz .LBB0_1209
	s_load_dwordx2 s[22:23], s[0:1], 0xf0
	s_and_b32 s6, s90, 0xffffffc0
	v_mbcnt_hi_u32_b32 v51, -1, v254
	v_mov_b32_e32 v52, v51
	s_waitcnt lgkmcnt(0)
	s_add_u32 s3, s22, 0x421d8000
	s_addc_u32 s52, s23, 0
	s_add_u32 s24, s22, 0x3efd8000
	s_addc_u32 s25, s23, 0
	s_add_u32 s26, s22, 0x441d8000
	s_addc_u32 s27, s23, 0
	s_cmpk_gt_u32 s90, 0xff
	v_add_u32_e32 v50, s6, v52
	v_and_b32_e32 v53, 63, v52
	s_mov_b64 s[6:7], -1
	s_cbranch_scc0 .LBB0_1178
	s_lshl_b32 s6, s92, 2
	s_add_i32 s6, s6, s33
	s_add_i32 s53, s6, 0x47fc
	s_mov_b32 s99, 0
	s_cmpk_gt_i32 s92, 0x2ff
	v_lshlrev_b32_e32 v54, 2, v53
	s_cbranch_scc1 .LBB0_1169
	v_lshlrev_b32_e32 v0, 4, v52
	s_mov_b32 s14, 0x2aaaaaab
	v_and_b32_e32 v20, 0x70, v0
	v_mul_hi_i32 v0, v50, s14
	v_lshrrev_b32_e32 v1, 31, v0
	v_ashrrev_i32_e32 v0, 2, v0
	v_add_u32_e32 v56, v0, v1
	v_add_u32_e32 v1, 0x200, v50
	v_mul_hi_i32 v2, v1, s14
	v_lshrrev_b32_e32 v3, 31, v2
	v_ashrrev_i32_e32 v2, 2, v2
	v_add_u32_e32 v57, v2, v3
	v_add_u32_e32 v3, 0x400, v50
	v_mul_hi_i32 v4, v3, s14
	v_mul_lo_u32 v0, v56, 24
	v_lshrrev_b32_e32 v5, 31, v4
	v_ashrrev_i32_e32 v4, 2, v4
	v_sub_u32_e32 v0, v50, v0
	v_mul_lo_u32 v2, v57, 24
	v_add_u32_e32 v58, v4, v5
	v_mov_b32_e32 v23, 0
	v_lshlrev_b32_e32 v22, 3, v0
	v_sub_u32_e32 v2, v1, v2
	v_mul_lo_u32 v4, v58, 24
	s_movk_i32 s20, 0x190
	s_add_u32 s48, s22, 0x33d8000
	v_lshl_add_u64 v[26:27], v[22:23], 1, s[24:25]
	v_ashrrev_i32_e32 v29, 31, v22
	v_mov_b32_e32 v28, v22
	v_lshlrev_b32_e32 v22, 3, v2
	v_sub_u32_e32 v3, v3, v4
	v_mul_lo_u32 v61, v56, s20
	v_mul_lo_u32 v63, v57, s20
	v_mul_lo_u32 v65, v58, s20
	s_addc_u32 s49, s23, 0
	v_mov_b32_e32 v21, v23
	v_cmp_gt_i32_e64 s[6:7], 16, v0
	v_cmp_lt_i32_e64 s[8:9], 15, v0
	v_cmp_gt_i32_e64 s[10:11], 16, v2
	v_cmp_lt_i32_e64 s[12:13], 15, v2
	v_lshl_add_u64 v[30:31], v[22:23], 1, s[24:25]
	v_ashrrev_i32_e32 v33, 31, v22
	v_mov_b32_e32 v32, v22
	v_lshlrev_b32_e32 v22, 3, v3
	v_ashrrev_i32_e32 v59, 3, v50
	v_ashrrev_i32_e32 v60, 3, v1
	v_add_u32_e32 v1, 0, v61
	v_lshlrev_b32_e32 v62, 4, v0
	v_add_u32_e32 v0, 0, v63
	v_lshlrev_b32_e32 v64, 4, v2
	v_add_u32_e32 v2, 0, v65
	v_lshlrev_b32_e32 v66, 4, v3
	s_movk_i32 s20, 0x88
	s_add_u32 s54, s22, 0x233d8000
	s_movk_i32 s28, 0xff00
	v_lshl_add_u64 v[24:25], s[26:27], 0, v[20:21]
	s_mov_b32 s21, 0
	v_add_u32_e32 v21, 0, v20
	v_and_b32_e32 v55, 0x7c, v54
	v_cmp_gt_i32_e64 s[14:15], 16, v3
	v_cmp_lt_i32_e64 s[16:17], 15, v3
	v_lshl_add_u64 v[34:35], v[22:23], 1, s[24:25]
	v_ashrrev_i32_e32 v37, 31, v22
	v_mov_b32_e32 v36, v22
	v_mul_lo_u32 v67, v59, s20
	v_mul_lo_u32 v68, v60, s20
	s_addc_u32 s55, s23, 0
	s_mov_b32 s29, -1
	v_add_u32_e32 v69, v1, v62
	v_add_u32_e32 v70, v0, v64
	v_add_u32_e32 v71, v2, v66
	s_movk_i32 s63, 0x6400
	s_movk_i32 s64, 0x2000
	s_movk_i32 s65, 0x4000
	s_movk_i32 s66, 0x6000
	s_mov_b32 s67, 0x8000
	s_mov_b32 s68, 0xa000
	s_mov_b32 s69, 0xc000
	s_mov_b32 s70, 0xe000
	s_mov_b32 s71, 0x10000
	s_mov_b32 s72, 0x12000
	s_mov_b32 s73, 0x14000
	s_mov_b32 s74, 0x16000
	s_mov_b32 s75, 0x18000
	s_mov_b32 s76, 0x1a000
	s_mov_b32 s77, 0x1c000
	s_mov_b32 s78, 0x1e000
	s_mov_b32 s79, s92
	s_branch .LBB0_1138

.Lsx_e_8:
	s_cmp_lt_u32 s33, 4
	s_cbranch_scc1 .LBB0_1669
	s_lshl_b32 s16, s92, 2
	s_add_i32 s16, s16, s33
	s_add_i32 s16, s16, 0xd7fc
	s_mov_b32 s17, 8
	s_branch .Lsx_conv_B
.Lsx_e_9:
	s_cmp_lt_u32 s33, 4
	s_cbranch_scc1 .LBB0_1740
	s_lshl_b32 s16, s92, 2
	s_add_i32 s16, s16, s33
	s_add_i32 s16, s16, 0xdbfc
	s_mov_b32 s17, 9
	s_branch .Lsx_conv_B
.Lsx_e_10:
	s_cmp_lt_u32 s33, 4
	s_cbranch_scc1 .LBB0_1811
	s_lshl_b32 s16, s92, 2
	s_add_i32 s16, s16, s33
	s_add_i32 s16, s16, 0xdffc
	s_mov_b32 s17, 10
	s_branch .Lsx_conv_B
.Lsx_e_11:
	s_cmp_lt_u32 s33, 4
	s_cbranch_scc1 .LBB0_1902
	s_lshl_b32 s16, s92, 2
	s_add_i32 s16, s16, s33
	s_add_i32 s16, s16, 0xe3fc
	s_mov_b32 s17, 11
	s_branch .Lsx_conv_B
.Lsx_e_12:
	s_cmp_lt_u32 s33, 4
	s_cbranch_scc1 .LBB0_2330
	s_lshl_b32 s16, s92, 2
	s_add_i32 s16, s16, s33
	s_add_i32 s16, s16, 0xe7fc
	s_mov_b32 s17, 12
	s_branch .Lsx_conv_B
.Lsx_e_13:
	s_cmp_lt_u32 s33, 4
	s_cbranch_scc1 .LBB0_2476
	s_lshl_b32 s16, s92, 2
	s_add_i32 s16, s16, s33
	s_add_i32 s16, s16, 0xebfc
	s_mov_b32 s17, 13
	s_branch .Lsx_conv_B
.Lsx_e_14:
	s_cmp_lt_u32 s33, 4
	s_cbranch_scc1 .LBB0_2602
	s_lshl_b32 s16, s92, 2
	s_add_i32 s16, s16, s33
	s_add_i32 s16, s16, 0xeffc
	s_mov_b32 s17, 14
	s_branch .Lsx_conv_B
.Lsx_e_15:
	s_cmp_lt_u32 s33, 4
	s_cbranch_scc1 .LBB0_2682
	s_lshl_b32 s16, s92, 2
	s_add_i32 s16, s16, s33
	s_add_i32 s16, s16, 0xf3fc
	s_mov_b32 s17, 15
	s_branch .Lsx_conv_B

.LsxB_1168:
	s_lshl_b64 s[44:45], s[44:45], 2
	s_waitcnt lgkmcnt(0)
	s_add_u32 s20, s42, s44
	s_addc_u32 s43, s43, s45
	s_bfe_u32 s44, s16, 0x70003
	s_lshl_b32 s42, s44, 17
	s_add_u32 s42, s20, s42
	s_addc_u32 s43, s43, 0
	v_lshlrev_b32_e32 v212, 2, v212
	v_lshl_add_u64 v[144:145], s[42:43], 0, v[212:213]
	v_add_co_u32_e32 v88, vcc, 0x2000, v144
	global_load_dwordx4 v[84:87], v212, s[42:43] nt
	s_nop 0
	v_addc_co_u32_e32 v89, vcc, 0, v145, vcc
	v_add_co_u32_e32 v92, vcc, 0x4000, v144
	v_mov_b32_e32 v200, v213
	s_nop 0
	v_addc_co_u32_e32 v93, vcc, 0, v145, vcc
	v_add_co_u32_e32 v96, vcc, 0x6000, v144
	global_load_dwordx4 v[88:91], v[88:89], off nt
	s_nop 0
	global_load_dwordx4 v[92:95], v[92:93], off nt
	v_addc_co_u32_e32 v97, vcc, 0, v145, vcc
	v_add_co_u32_e32 v100, vcc, 0x8000, v144
	v_mov_b32_e32 v201, v213
	s_nop 0
	v_addc_co_u32_e32 v101, vcc, 0, v145, vcc
	v_add_co_u32_e32 v104, vcc, 0xa000, v144
	global_load_dwordx4 v[96:99], v[96:97], off nt
	s_nop 0
	global_load_dwordx4 v[100:103], v[100:101], off nt
	v_addc_co_u32_e32 v105, vcc, 0, v145, vcc
	v_add_co_u32_e32 v108, vcc, 0xc000, v144
	v_mov_b32_e32 v202, v213
	s_nop 0
	v_addc_co_u32_e32 v109, vcc, 0, v145, vcc
	v_add_co_u32_e32 v112, vcc, 0xe000, v144
	global_load_dwordx4 v[104:107], v[104:105], off nt
	s_nop 0
	global_load_dwordx4 v[108:111], v[108:109], off nt
	v_addc_co_u32_e32 v113, vcc, 0, v145, vcc
	v_add_co_u32_e32 v116, vcc, 0x10000, v144
	v_mov_b32_e32 v203, v213
	s_nop 0
	v_addc_co_u32_e32 v117, vcc, 0, v145, vcc
	v_add_co_u32_e32 v120, vcc, 0x12000, v144
	global_load_dwordx4 v[112:115], v[112:113], off nt
	s_nop 0
	global_load_dwordx4 v[116:119], v[116:117], off nt
	v_addc_co_u32_e32 v121, vcc, 0, v145, vcc
	v_add_co_u32_e32 v124, vcc, 0x14000, v144
	v_mov_b32_e32 v204, v213
	s_nop 0
	v_addc_co_u32_e32 v125, vcc, 0, v145, vcc
	v_add_co_u32_e32 v128, vcc, 0x16000, v144
	global_load_dwordx4 v[120:123], v[120:121], off nt
	s_nop 0
	global_load_dwordx4 v[124:127], v[124:125], off nt
	v_addc_co_u32_e32 v129, vcc, 0, v145, vcc
	v_add_co_u32_e32 v132, vcc, 0x18000, v144
	v_mov_b32_e32 v205, v213
	s_nop 0
	v_addc_co_u32_e32 v133, vcc, 0, v145, vcc
	v_add_co_u32_e32 v136, vcc, 0x1a000, v144
	global_load_dwordx4 v[128:131], v[128:129], off nt
	s_nop 0
	global_load_dwordx4 v[132:135], v[132:133], off nt
	v_addc_co_u32_e32 v137, vcc, 0, v145, vcc
	v_add_co_u32_e32 v140, vcc, 0x1c000, v144
	v_mov_b32_e32 v206, v213
	s_nop 0
	v_addc_co_u32_e32 v141, vcc, 0, v145, vcc
	global_load_dwordx4 v[136:139], v[136:137], off nt
	s_nop 0
	global_load_dwordx4 v[140:143], v[140:141], off nt
	v_add_co_u32_e32 v144, vcc, 0x1e000, v144
	v_mov_b32_e32 v207, v213
	s_nop 0
	v_addc_co_u32_e32 v145, vcc, 0, v145, vcc
	global_load_dwordx4 v[144:147], v[144:145], off nt
	v_mov_b32_e32 v208, v213
	v_mov_b32_e32 v209, v213
	v_mov_b32_e32 v210, v213
	v_mov_b32_e32 v211, v213
	s_mul_i32 s20, s40, s44
	s_waitcnt vmcnt(15)
	v_mul_f32_e32 v212, s41, v84
	v_ashrrev_i32_e32 v215, 31, v214
	v_lshl_add_u64 v[214:215], s[20:21], 0, v[214:215]
	v_lshl_add_u64 v[214:215], v[214:215], 4, s[38:39]
	s_waitcnt vmcnt(14)
	v_mul_f32_e32 v84, s41, v88
	v_cvt_pk_fp8_f32 v200, v212, v84
	s_waitcnt vmcnt(13)
	v_mul_f32_e32 v88, s41, v92
	s_waitcnt vmcnt(12)
	v_mul_f32_e32 v92, s41, v96
	s_waitcnt vmcnt(11)
	v_mul_f32_e32 v212, s41, v100
	v_cvt_pk_fp8_f32 v200, v88, v92 op_sel:[0,0,1]
	s_waitcnt vmcnt(10)
	v_mul_f32_e32 v84, s41, v104
	v_cvt_pk_fp8_f32 v201, v212, v84
	s_waitcnt vmcnt(9)
	v_mul_f32_e32 v212, s41, v108
	s_waitcnt vmcnt(8)
	v_mul_f32_e32 v84, s41, v112
	v_cvt_pk_fp8_f32 v201, v212, v84 op_sel:[0,0,1]
	s_waitcnt vmcnt(7)
	v_mul_f32_e32 v212, s41, v116
	s_waitcnt vmcnt(6)
	v_mul_f32_e32 v84, s41, v120
	v_cvt_pk_fp8_f32 v202, v212, v84
	s_waitcnt vmcnt(5)
	v_mul_f32_e32 v88, s41, v124
	s_waitcnt vmcnt(4)
	v_mul_f32_e32 v92, s41, v128
	s_waitcnt vmcnt(3)
	v_mul_f32_e32 v212, s41, v132
	v_cvt_pk_fp8_f32 v202, v88, v92 op_sel:[0,0,1]
	v_mul_f32_e32 v88, s41, v97
	s_waitcnt vmcnt(2)
	v_mul_f32_e32 v84, s41, v136
	v_cvt_pk_fp8_f32 v203, v212, v84
	s_waitcnt vmcnt(1)
	v_mul_f32_e32 v212, s41, v140
	s_waitcnt vmcnt(0)
	v_mul_f32_e32 v84, s41, v144
	v_cvt_pk_fp8_f32 v203, v212, v84 op_sel:[0,0,1]
	v_mul_f32_e32 v212, s41, v85
	v_mul_f32_e32 v84, s41, v89
	v_cvt_pk_fp8_f32 v204, v212, v84
	v_mul_f32_e32 v212, s41, v101
	v_mul_f32_e32 v84, s41, v105
	v_cvt_pk_fp8_f32 v205, v212, v84
	v_mul_f32_e32 v212, s41, v109
	v_mul_f32_e32 v84, s41, v113
	v_mul_f32_e32 v85, s41, v93
	v_cvt_pk_fp8_f32 v205, v212, v84 op_sel:[0,0,1]
	v_mul_f32_e32 v212, s41, v117
	v_mul_f32_e32 v84, s41, v121
	v_cvt_pk_fp8_f32 v206, v212, v84
	v_mul_f32_e32 v212, s41, v133
	v_mul_f32_e32 v84, s41, v137
	v_cvt_pk_fp8_f32 v207, v212, v84
	v_mul_f32_e32 v212, s41, v141
	v_mul_f32_e32 v84, s41, v145
	v_cvt_pk_fp8_f32 v204, v85, v88 op_sel:[0,0,1]
	v_cvt_pk_fp8_f32 v207, v212, v84 op_sel:[0,0,1]
	v_mul_f32_e32 v212, s41, v86
	v_mul_f32_e32 v84, s41, v90
	v_cvt_pk_fp8_f32 v208, v212, v84
	v_mul_f32_e32 v212, s41, v102
	v_mul_f32_e32 v84, s41, v106
	v_cvt_pk_fp8_f32 v209, v212, v84
	v_mul_f32_e32 v212, s41, v110
	v_mul_f32_e32 v84, s41, v114
	v_mul_f32_e32 v85, s41, v125
	v_cvt_pk_fp8_f32 v209, v212, v84 op_sel:[0,0,1]
	v_mul_f32_e32 v212, s41, v118
	v_mul_f32_e32 v84, s41, v122
	v_cvt_pk_fp8_f32 v210, v212, v84
	v_mul_f32_e32 v212, s41, v134
	v_mul_f32_e32 v84, s41, v138
	v_cvt_pk_fp8_f32 v211, v212, v84
	v_mul_f32_e32 v88, s41, v129
	v_cvt_pk_fp8_f32 v206, v85, v88 op_sel:[0,0,1]
	v_mul_f32_e32 v85, s41, v94
	v_mul_f32_e32 v86, s41, v98
	v_cvt_pk_fp8_f32 v208, v85, v86 op_sel:[0,0,1]
	v_mul_f32_e32 v85, s41, v126
	v_mul_f32_e32 v86, s41, v130
	v_mul_f32_e32 v212, s41, v142
	v_mul_f32_e32 v84, s41, v146
	v_cvt_pk_fp8_f32 v210, v85, v86 op_sel:[0,0,1]
	v_cvt_pk_fp8_f32 v211, v212, v84 op_sel:[0,0,1]
	v_mul_f32_e32 v212, s41, v87
	v_mul_f32_e32 v85, s41, v91
	v_mov_b32_e32 v84, v213
	v_cvt_pk_fp8_f32 v84, v212, v85
	v_mul_f32_e32 v212, s41, v103
	v_mul_f32_e32 v88, s41, v107
	v_mov_b32_e32 v85, v213
	v_cvt_pk_fp8_f32 v85, v212, v88
	v_mul_f32_e32 v86, s41, v95
	v_mul_f32_e32 v87, s41, v99
	v_cvt_pk_fp8_f32 v84, v86, v87 op_sel:[0,0,1]
	v_mul_f32_e32 v212, s41, v111
	v_mul_f32_e32 v86, s41, v115
	v_cvt_pk_fp8_f32 v85, v212, v86 op_sel:[0,0,1]
	v_mul_f32_e32 v212, s41, v119
	v_mul_f32_e32 v87, s41, v123
	v_mov_b32_e32 v86, v213
	v_cvt_pk_fp8_f32 v86, v212, v87
	v_mul_f32_e32 v212, s41, v135
	v_mul_f32_e32 v90, s41, v139
	v_mov_b32_e32 v87, v213
	v_cvt_pk_fp8_f32 v87, v212, v90
	v_mul_f32_e32 v88, s41, v127
	v_mul_f32_e32 v89, s41, v131
	v_cvt_pk_fp8_f32 v86, v88, v89 op_sel:[0,0,1]
	v_mul_f32_e32 v212, s41, v143
	v_mul_f32_e32 v88, s41, v147
	v_cvt_pk_fp8_f32 v87, v212, v88 op_sel:[0,0,1]
	global_store_dwordx4 v[214:215], v[200:203], off
	global_store_dwordx4 v[214:215], v[204:207], off offset:16
	global_store_dwordx4 v[214:215], v[208:211], off offset:32
	global_store_dwordx4 v[214:215], v[84:87], off offset:48
	s_cmp_eq_u32 s17, 8
	s_cbranch_scc1 .LBB0_1669
	s_cmp_eq_u32 s17, 9
	s_cbranch_scc1 .LBB0_1740
	s_cmp_eq_u32 s17, 10
	s_cbranch_scc1 .LBB0_1811
	s_cmp_eq_u32 s17, 11
	s_cbranch_scc1 .LBB0_1902
	s_cmp_eq_u32 s17, 12
	s_cbranch_scc1 .LBB0_2330
	s_cmp_eq_u32 s17, 13
	s_cbranch_scc1 .LBB0_2476
	s_cmp_eq_u32 s17, 14
	s_cbranch_scc1 .LBB0_2602
	s_cmp_eq_u32 s17, 15
	s_cbranch_scc1 .LBB0_2682
	s_branch .LBB0_2682

.LBB0_2361:
	s_andn2_b64 vcc, exec, s[8:9]
	s_cbranch_vccnz .LBB0_2423
	s_load_dwordx2 s[14:15], s[0:1], 0xf0
	s_and_b32 s3, s90, 0xffffffc0
	s_waitcnt vmcnt(0)
	v_mbcnt_hi_u32_b32 v24, -1, v254
	v_mov_b32_e32 v25, v24
	s_waitcnt lgkmcnt(0)
	s_add_u32 s8, s14, 0x469d8000
	s_addc_u32 s9, s15, 0
	s_add_u32 s10, s14, 0x461d8000
	s_addc_u32 s11, s15, 0
	s_cmpk_gt_u32 s90, 0xff
	v_add_u32_e32 v26, s3, v25
	v_and_b32_e32 v27, 63, v25
	s_mov_b64 s[12:13], -1
	s_cbranch_scc0 .LBB0_2395
	s_lshl_b32 s3, s92, 2
	s_add_i32 s3, s3, s33
	s_add_i32 s3, s3, 0xf7fc
	s_mov_b32 s99, 0
	s_cmpk_gt_i32 s92, 0x5ff
	v_lshlrev_b32_e32 v28, 2, v27
	s_cbranch_scc1 .LBB0_2386
	v_ashrrev_i32_e32 v0, 31, v26
	v_lshrrev_b32_e32 v0, 29, v0
	v_add_u32_e32 v0, v26, v0
	v_ashrrev_i32_e32 v29, 3, v0
	v_and_b32_e32 v0, -8, v0
	s_movk_i32 s12, 0x90
	v_sub_u32_e32 v1, v26, v0
	v_ashrrev_i32_e32 v30, 3, v26
	v_lshlrev_b32_e32 v0, 3, v25
	v_mul_lo_u32 v31, v29, s12
	s_movk_i32 s12, 0x88
	s_add_u32 s28, s14, 0x33d8000
	v_lshlrev_b32_e32 v8, 3, v1
	v_and_b32_e32 v0, 56, v0
	v_mul_lo_u32 v33, v30, s12
	v_lshlrev_b32_e32 v3, 4, v25
	s_addc_u32 s29, s15, 0
	v_ashrrev_i32_e32 v9, 31, v8
	v_mov_b32_e32 v11, 0
	v_add_u32_e32 v2, 0, v31
	v_lshlrev_b32_e32 v32, 4, v1
	v_add_u32_e32 v1, 0, v33
	v_and_b32_e32 v34, 0x70, v3
	v_lshlrev_b32_e32 v10, 1, v0
	s_add_u32 s30, s14, 0x233d8000
	s_movk_i32 s34, 0x2400
	s_mov_b32 s13, 0
	v_lshl_add_u64 v[12:13], v[8:9], 1, s[8:9]
	v_lshl_add_u64 v[14:15], s[10:11], 0, v[10:11]
	v_and_b32_e32 v35, 0x7c, v28
	s_addc_u32 s31, s15, 0
	v_lshlrev_b32_e32 v16, 1, v0
	v_mov_b32_e32 v17, v11
	v_add_u32_e32 v36, v2, v32
	v_add3_u32 v37, v1, v34, s34
	s_movk_i32 s35, 0x2000
	s_movk_i32 s36, 0x4000
	s_movk_i32 s37, 0x6000
	s_mov_b32 s38, 0x8000
	s_mov_b32 s39, 0xa000
	s_mov_b32 s40, 0xc000
	s_mov_b32 s41, 0xe000
	s_mov_b32 s42, 0x10000
	s_mov_b32 s43, 0x12000
	s_mov_b32 s44, 0x14000
	s_mov_b32 s45, 0x16000
	s_mov_b32 s46, 0x18000
	s_mov_b32 s47, 0x1a000
	s_mov_b32 s48, 0x1c000
	s_mov_b32 s49, 0x1e000
	v_mov_b32_e32 v38, 0x80
	s_mov_b32 s50, s92
	s_ashr_i32 s18, s50, 1
	s_cmpk_gt_i32 s18, 0x1ff
	s_mov_b64 s[16:17], -1
	s_cbranch_scc0 .LBB0_2367
	s_branch .LBB0_2366
